# GLA local-state phase: low-rank gate input rows 1-6 of each item loaded together with row 0 at the item top (fresh registers) instead of one round trip per row
# baseline (speedup 1.0000x reference)
; __device__ __forceinline__ void gla_b(const Args& a, int l, int row0, int h, LAS unsigned char* L, int tid) {
;     ...
;     const float* ALRP = (const float*)(a.ws + WS_ALRP); const float* ssq = (const float*)(a.ws + WS_SSQ) + (size_t)(2 * l) * M;
;     const int d = tid & 63, tg = __builtin_amdgcn_readfirstlane(tid >> 6);
;     float wa[16];
; #pragma unroll
;     for (int j = 0; j < 16; ++j) wa[j] = a.in[7][((size_t)l * 16 + j) * 256 + h * 64 + d];
;     const float ba = a.in[8][l * 256 + h * 64 + d];
;     float bl[8]; float run = 0.f;
; #pragma unroll
;     for (int i = 0; i < 8; ++i) {
;         const int row = row0 + 8 * tg + i;
;         const float sc = rsqrtf(ssq[row] * (1.0f / D) + EPS);
;         const f32x4 a0 = *(const f32x4*)(ALRP + (size_t)row * 16), a1 = *(const f32x4*)(ALRP + (size_t)row * 16 + 4), a2 = *(const f32x4*)(ALRP + (size_t)row * 16 + 8), a3 = *(const f32x4*)(ALRP + (size_t)row * 16 + 12);
;         float x = (a0[0] * wa[0] + a0[1] * wa[1]) + (a0[2] * wa[2] + a0[3] * wa[3]);
;         x += (a1[0] * wa[4] + a1[1] * wa[5]) + (a1[2] * wa[6] + a1[3] * wa[7]);
;         x += (a2[0] * wa[8] + a2[1] * wa[9]) + (a2[2] * wa[10] + a2[3] * wa[11]);
;         x += (a3[0] * wa[12] + a3[1] * wa[13]) + (a3[2] * wa[14] + a3[3] * wa[15]);
;         x = x * sc + ba;
;         const float ls = fminf(x, 0.f) - __logf(1.0f + __expf(-fabsf(x)));
;         run += ls * (1.0f / 16.0f); bl[i] = run;
;     }
; __device__ __forceinline__ void gla_a_item(const Args& a, int l, int item, LAS unsigned char* L, int tid, int wave, int lane) {
;     const int ch = item >> 2, h = item & 3, row0 = ch * 64;
;     const u32x4 kr = *(const u32x4*)((const bf16_t*)(a.ws + WS_GK) + (size_t)(row0 + (tid >> 3)) * 256 + h * 64 + 8 * (tid & 7));
;     const bf16_t* vp_ = (const bf16_t*)(a.ws + WS_GV) + (size_t)(row0 + (tid >> 3)) * 512 + h * 128 + 16 * (tid & 7);
;     const u32x4 pv0 = *(const u32x4*)vp_, pv1 = *(const u32x4*)(vp_ + 8);
;     gla_b(a, l, row0, h, L, tid);
.LBB0_903:
	s_and_b32 s4, s15, 3
	s_and_b32 s5, s14, 0xffffffc0
	v_add_u32_e32 v2, s5, v40
	s_lshl_b32 s8, s4, 6
	v_readlane_b32 s52, v249, 0
	v_ashrrev_i32_e32 v3, 31, v2
	v_readlane_b32 s6, v247, 26
	v_or_b32_e32 v14, s8, v41
	v_mov_b32_e32 v15, v1
	v_readlane_b32 s66, v249, 14
	v_readlane_b32 s67, v249, 15
	v_lshlrev_b64 v[4:5], 9, v[2:3]
	v_lshlrev_b64 v[2:3], 10, v[2:3]
	v_readlane_b32 s7, v247, 27
	v_lshl_add_u64 v[14:15], v[14:15], 2, s[66:67]
	v_lshl_add_u64 v[4:5], s[18:19], 0, v[4:5]
	s_lshl_b32 s82, s4, 7
	v_lshl_add_u64 v[2:3], s[6:7], 0, v[2:3]
	v_add_co_u32_e64 v16, s[6:7], s25, v14
	v_lshl_add_u64 v[4:5], v[4:5], 0, s[82:83]
	s_lshl_b32 s82, s4, 8
	v_addc_co_u32_e64 v17, s[6:7], 0, v15, s[6:7]
	v_lshl_add_u64 v[2:3], v[2:3], 0, s[82:83]
	v_mov_b32_e32 v37, v1
	v_readfirstlane_b32 s16, v38
	v_add_co_u32_e64 v18, s[6:7], s23, v14
	v_lshl_add_u64 v[4:5], v[4:5], 0, v[0:1]
	v_lshl_add_u64 v[2:3], v[2:3], 0, v[36:37]
	v_addc_co_u32_e64 v19, s[6:7], 0, v15, s[6:7]
	s_movk_i32 s4, 0x3000
	s_ashr_i32 s17, s16, 6
	global_load_dwordx4 v[10:13], v[4:5], off
	global_load_dwordx4 v[6:9], v[2:3], off
	s_nop 0
	global_load_dwordx4 v[2:5], v[2:3], off offset:16
	s_nop 0
	global_load_dword v37, v[14:15], off
	global_load_dword v62, v[14:15], off offset:1024
	global_load_dword v31, v[14:15], off offset:2048
	global_load_dword v61, v[14:15], off offset:3072
	v_add_co_u32_e64 v14, s[6:7], s4, v14
	s_lshl_b32 s4, s17, 3
	s_add_i32 s12, s4, s5
	v_addc_co_u32_e64 v15, s[6:7], 0, v15, s[6:7]
	s_ashr_i32 s13, s12, 31
	s_lshl_b64 s[4:5], s[12:13], 2
	v_readlane_b32 s6, v248, 17
	v_readlane_b32 s53, v249, 1
	v_readlane_b32 s54, v249, 2
	v_readlane_b32 s55, v249, 3
	v_readlane_b32 s56, v249, 4
	v_readlane_b32 s57, v249, 5
	v_readlane_b32 s58, v249, 6
	v_readlane_b32 s59, v249, 7
	v_readlane_b32 s60, v249, 8
	v_readlane_b32 s61, v249, 9
	v_readlane_b32 s62, v249, 10
	v_readlane_b32 s63, v249, 11
	v_readlane_b32 s64, v249, 12
	v_readlane_b32 s65, v249, 13
	v_readlane_b32 s7, v248, 18
	s_add_u32 s6, s6, s4
	v_readlane_b32 s52, v249, 16
	s_addc_u32 s7, s7, s5
	s_lshl_b64 s[4:5], s[12:13], 6
	global_load_dword v63, v[18:19], off offset:-4096
	global_load_dword v66, v[16:17], off offset:1024
	global_load_dword v64, v[16:17], off offset:2048
	global_load_dword v68, v[16:17], off offset:3072
	global_load_dword v65, v[18:19], off
	global_load_dword v70, v[18:19], off offset:1024
	global_load_dword v67, v[18:19], off offset:2048
	global_load_dword v73, v[18:19], off offset:3072
	global_load_dword v71, v[14:15], off
	global_load_dword v74, v[14:15], off offset:1024
	global_load_dword v69, v[14:15], off offset:2048
	global_load_dword v72, v[14:15], off offset:3072
	v_or_b32_e32 v14, s8, v42
	v_mov_b32_e32 v15, v1
	v_readlane_b32 s53, v249, 17
	s_add_u32 s4, s68, s4
	s_addc_u32 s5, s69, s5
	v_lshl_add_u64 v[14:15], v[14:15], 2, s[52:53]
	global_load_dword v75, v[14:15], off
	s_nop 0
	global_load_dwordx4 v[14:17], v1, s[4:5] offset:48
	global_load_dwordx4 v[18:21], v1, s[4:5] offset:32
	global_load_dwordx4 v[22:25], v1, s[4:5] offset:16
	global_load_dwordx4 v[26:29], v1, s[4:5]
	global_load_dwordx4 v[102:105], v1, s[4:5] offset:112
	global_load_dwordx4 v[98:101], v1, s[4:5] offset:96
	global_load_dwordx4 v[94:97], v1, s[4:5] offset:80
	global_load_dwordx4 v[90:93], v1, s[4:5] offset:64
	global_load_dwordx4 v[118:121], v1, s[4:5] offset:176
	global_load_dwordx4 v[114:117], v1, s[4:5] offset:160
	global_load_dwordx4 v[110:113], v1, s[4:5] offset:144
	global_load_dwordx4 v[106:109], v1, s[4:5] offset:128
	global_load_dwordx4 v[134:137], v1, s[4:5] offset:240
	global_load_dwordx4 v[130:133], v1, s[4:5] offset:224
	global_load_dwordx4 v[126:129], v1, s[4:5] offset:208
	global_load_dwordx4 v[122:125], v1, s[4:5] offset:192
	global_load_dwordx4 v[150:153], v1, s[4:5] offset:304
	global_load_dwordx4 v[146:149], v1, s[4:5] offset:288
	global_load_dwordx4 v[142:145], v1, s[4:5] offset:272
	global_load_dwordx4 v[138:141], v1, s[4:5] offset:256
	global_load_dwordx4 v[178:181], v1, s[4:5] offset:368
	global_load_dwordx4 v[174:177], v1, s[4:5] offset:352
	global_load_dwordx4 v[158:161], v1, s[4:5] offset:336
	global_load_dwordx4 v[154:157], v1, s[4:5] offset:320
	global_load_dwordx4 v[194:197], v1, s[4:5] offset:432
	global_load_dwordx4 v[190:193], v1, s[4:5] offset:416
	global_load_dwordx4 v[186:189], v1, s[4:5] offset:400
	global_load_dwordx4 v[182:185], v1, s[4:5] offset:384
	s_mov_b32 s40, 0x3a800000
	s_mov_b32 s13, 0xbfb8aa3b
	s_mov_b32 s22, 0x3f317217
	s_or_b32 s4, s12, 1
	s_ashr_i32 s5, s4, 31
	s_mov_b32 s36, 0x7f800000
	s_lshl_b64 s[4:5], s[4:5], 6
	s_add_u32 s4, s68, s4
	s_addc_u32 s5, s69, s5
	v_readlane_b32 s54, v249, 18
	v_readlane_b32 s55, v249, 19
	v_readlane_b32 s56, v249, 20
	v_readlane_b32 s57, v249, 21
	v_readlane_b32 s58, v249, 22
	v_readlane_b32 s59, v249, 23
	v_readlane_b32 s60, v249, 24
	v_readlane_b32 s61, v249, 25
	v_readlane_b32 s62, v249, 26
	v_readlane_b32 s63, v249, 27
	v_readlane_b32 s64, v249, 28
	v_readlane_b32 s65, v249, 29
	v_readlane_b32 s66, v249, 30
	v_readlane_b32 s67, v249, 31
	s_waitcnt vmcnt(27)
	v_mul_f32_e32 v15, v74, v15
	s_waitcnt vmcnt(26)
	v_mul_f32_e32 v19, v70, v19
	s_waitcnt vmcnt(25)
	v_mul_f32_e32 v23, v66, v23
	s_waitcnt vmcnt(24)
	v_mul_f32_e32 v27, v62, v27
	v_fmac_f32_e32 v27, v37, v26
	v_mul_f32_e32 v26, v61, v29
	v_fmac_f32_e32 v23, v63, v22
	v_mul_f32_e32 v22, v68, v25
	v_fmac_f32_e32 v26, v31, v28
	v_fmac_f32_e32 v22, v64, v24
	v_fmac_f32_e32 v19, v65, v18
	v_mul_f32_e32 v18, v73, v21
	v_add_f32_e32 v26, v27, v26
	v_add_f32_e32 v22, v23, v22
	v_fmac_f32_e32 v18, v67, v20
	v_fmac_f32_e32 v15, v71, v14
	v_mul_f32_e32 v14, v72, v17
	v_add_f32_e32 v22, v26, v22
	v_add_f32_e32 v18, v19, v18
	v_fmac_f32_e32 v14, v69, v16
	v_add_f32_e32 v18, v22, v18
	v_add_f32_e32 v14, v15, v14
	v_add_f32_e32 v24, v18, v14
	global_load_dwordx4 v[14:17], v1, s[6:7] offset:16
	global_load_dwordx4 v[18:21], v1, s[6:7]
	s_mov_b32 s6, 0x358637bd
	v_mov_b64_e32 v[22:23], s[6:7]
	s_waitcnt vmcnt(1)
; __device__ __forceinline__ void gla_b(const Args& a, int l, int row0, int h, LAS unsigned char* L, int tid) {
;     ...
;     for (int i = 0; i < 8; ++i) {
;         const int row = row0 + 8 * tg + i;
;         const float sc = rsqrtf(ssq[row] * (1.0f / D) + EPS);
;         const f32x4 a0 = *(const f32x4*)(ALRP + (size_t)row * 16), a1 = *(const f32x4*)(ALRP + (size_t)row * 16 + 4), a2 = *(const f32x4*)(ALRP + (size_t)row * 16 + 8), a3 = *(const f32x4*)(ALRP + (size_t)row * 16 + 12);
;         float x = (a0[0] * wa[0] + a0[1] * wa[1]) + (a0[2] * wa[2] + a0[3] * wa[3]);
;         x += (a1[0] * wa[4] + a1[1] * wa[5]) + (a1[2] * wa[6] + a1[3] * wa[7]);
;         x += (a2[0] * wa[8] + a2[1] * wa[9]) + (a2[2] * wa[10] + a2[3] * wa[11]);
;         x += (a3[0] * wa[12] + a3[1] * wa[13]) + (a3[2] * wa[14] + a3[3] * wa[15]);
;         x = x * sc + ba;
;         const float ls = fminf(x, 0.f) - __logf(1.0f + __expf(-fabsf(x)));
;         run += ls * (1.0f / 16.0f); bl[i] = run;
;     }
	v_pk_fma_f32 v[14:15], v[14:15], s[40:41], v[22:23] op_sel_hi:[1,0,0]
	s_waitcnt vmcnt(0)
	v_pk_fma_f32 v[18:19], v[18:19], s[40:41], v[22:23] op_sel_hi:[1,0,0]
	s_nop 0
	v_mul_f32_e32 v25, 0x4b800000, v18
	v_cmp_gt_f32_e64 s[8:9], s3, v18
	v_cmp_gt_f32_e64 s[6:7], s3, v19
	s_nop 0
	v_cndmask_b32_e64 v18, v18, v25, s[8:9]
	v_rsq_f32_e32 v18, v18
	s_nop 0
	v_mul_f32_e32 v25, 0x45800000, v18
	v_cndmask_b32_e64 v18, v18, v25, s[8:9]
	v_fma_f32 v18, v18, v24, v75
	v_min_f32_e32 v24, 0, v18
	v_mul_f32_e64 v18, |v18|, s13
	v_exp_f32_e32 v18, v18
	s_nop 0
	v_add_f32_e32 v18, 1.0, v18
	v_cmp_gt_f32_e64 s[8:9], s3, v18
	s_nop 1
	v_cndmask_b32_e64 v25, 0, 32, s[8:9]
	v_ldexp_f32 v18, v18, v25
	v_log_f32_e32 v18, v18
	s_nop 0
	v_mul_f32_e32 v25, 0x3f317217, v18
	v_fma_f32 v25, v18, s22, -v25
	v_fmac_f32_e32 v25, 0x3377d1cf, v18
	v_fmac_f32_e32 v25, 0x3f317217, v18
	v_cmp_lt_f32_e64 s[10:11], |v18|, s36
	s_nop 1
	v_cndmask_b32_e64 v18, v18, v25, s[10:11]
	v_cndmask_b32_e64 v25, 0, v206, s[8:9]
	v_sub_f32_e32 v18, v18, v25
	v_sub_f32_e32 v18, v24, v18
	s_mov_b32 s8, 0x3d800000
	v_fma_f32 v76, v18, s8, 0
	v_mul_f32_e32 v18, 0x4b800000, v19
	v_cndmask_b32_e64 v18, v19, v18, s[6:7]
	v_rsq_f32_e32 v18, v18
	s_or_b32 s4, s12, 2
	s_ashr_i32 s5, s4, 31
	s_lshl_b64 s[4:5], s[4:5], 6
	v_mul_f32_e32 v19, 0x45800000, v18
	v_cndmask_b32_e64 v18, v18, v19, s[6:7]
	s_add_u32 s4, s68, s4
	s_addc_u32 s5, s69, s5
	s_waitcnt vmcnt(3)
	v_mul_f32_e32 v25, v74, v103
	v_fmac_f32_e32 v25, v71, v102
	s_waitcnt vmcnt(1)
	v_mul_f32_e32 v29, v68, v97
	s_waitcnt vmcnt(0)
	v_mul_f32_e32 v19, v62, v91
	v_mul_f32_e32 v28, v61, v93
	v_fmac_f32_e32 v19, v37, v90
	v_fmac_f32_e32 v28, v31, v92
	v_add_f32_e32 v19, v19, v28
	v_mul_f32_e32 v28, v66, v95
	v_fmac_f32_e32 v28, v63, v94
	v_fmac_f32_e32 v29, v64, v96
	v_add_f32_e32 v28, v28, v29
	v_add_f32_e32 v19, v19, v28
	v_mul_f32_e32 v28, v70, v99
	v_mul_f32_e32 v29, v73, v101
	v_fmac_f32_e32 v28, v65, v98
	v_fmac_f32_e32 v29, v67, v100
	v_mul_f32_e32 v24, v72, v105
	v_add_f32_e32 v28, v28, v29
	v_fmac_f32_e32 v24, v69, v104
	v_add_f32_e32 v19, v19, v28
	v_add_f32_e32 v24, v25, v24
	v_add_f32_e32 v19, v19, v24
	v_fma_f32 v18, v18, v19, v75
	v_min_f32_e32 v19, 0, v18
	v_mul_f32_e64 v18, |v18|, s13
	v_exp_f32_e32 v18, v18
	s_nop 0
	v_add_f32_e32 v18, 1.0, v18
	v_cmp_gt_f32_e64 s[6:7], s3, v18
	s_nop 1
	v_cndmask_b32_e64 v24, 0, 32, s[6:7]
	v_ldexp_f32 v18, v18, v24
	v_log_f32_e32 v18, v18
	s_nop 0
	v_mul_f32_e32 v24, 0x3f317217, v18
	v_fma_f32 v24, v18, s22, -v24
	v_fmac_f32_e32 v24, 0x3377d1cf, v18
	v_fmac_f32_e32 v24, 0x3f317217, v18
	v_cmp_lt_f32_e64 s[8:9], |v18|, s36
	s_nop 1
	v_cndmask_b32_e64 v18, v18, v24, s[8:9]
	v_cndmask_b32_e64 v24, 0, v206, s[6:7]
	v_sub_f32_e32 v18, v18, v24
	v_sub_f32_e32 v18, v19, v18
	v_fmamk_f32 v77, v18, 0x3d800000, v76
	s_or_b32 s4, s12, 3
	s_ashr_i32 s5, s4, 31
	s_lshl_b64 s[4:5], s[4:5], 6
	s_add_u32 s4, s68, s4
	s_addc_u32 s5, s69, s5
	s_waitcnt vmcnt(1)
	v_mul_f32_e32 v28, v68, v113
	s_waitcnt vmcnt(0)
	v_mul_f32_e32 v18, v62, v107
	v_mul_f32_e32 v19, v61, v109
	v_fmac_f32_e32 v18, v37, v106
	v_fmac_f32_e32 v19, v31, v108
	v_add_f32_e32 v18, v18, v19
	v_mul_f32_e32 v19, v66, v111
	v_fmac_f32_e32 v19, v63, v110
	v_fmac_f32_e32 v28, v64, v112
	v_add_f32_e32 v19, v19, v28
	v_add_f32_e32 v18, v18, v19
	v_mul_f32_e32 v19, v70, v115
	v_mul_f32_e32 v28, v73, v117
	v_fmac_f32_e32 v19, v65, v114
	v_fmac_f32_e32 v28, v67, v116
	v_add_f32_e32 v19, v19, v28
	v_add_f32_e32 v18, v18, v19
	v_mul_f32_e32 v19, v74, v119
	v_fmac_f32_e32 v19, v71, v118
	v_mul_f32_e32 v24, v72, v121
	v_fmac_f32_e32 v24, v69, v120
	v_add_f32_e32 v19, v19, v24
	v_add_f32_e32 v24, v18, v19
	v_pk_fma_f32 v[18:19], v[20:21], s[40:41], v[22:23] op_sel_hi:[1,0,0]
	s_nop 0
	v_mul_f32_e32 v20, 0x4b800000, v18
	v_cmp_gt_f32_e64 s[8:9], s3, v18
	v_cmp_gt_f32_e64 s[6:7], s3, v19
	s_nop 0
	v_cndmask_b32_e64 v18, v18, v20, s[8:9]
	v_rsq_f32_e32 v18, v18
	s_nop 0
	v_mul_f32_e32 v20, 0x45800000, v18
	v_cndmask_b32_e64 v18, v18, v20, s[8:9]
	v_fma_f32 v18, v18, v24, v75
	v_min_f32_e32 v20, 0, v18
	v_mul_f32_e64 v18, |v18|, s13
	v_exp_f32_e32 v18, v18
	s_nop 0
	v_add_f32_e32 v18, 1.0, v18
	v_cmp_gt_f32_e64 s[8:9], s3, v18
	s_nop 1
	v_cndmask_b32_e64 v21, 0, 32, s[8:9]
	v_ldexp_f32 v18, v18, v21
	v_log_f32_e32 v18, v18
	s_nop 0
	v_mul_f32_e32 v21, 0x3f317217, v18
	v_fma_f32 v21, v18, s22, -v21
	v_fmac_f32_e32 v21, 0x3377d1cf, v18
	v_fmac_f32_e32 v21, 0x3f317217, v18
	v_cmp_lt_f32_e64 s[10:11], |v18|, s36
	s_nop 1
	v_cndmask_b32_e64 v18, v18, v21, s[10:11]
	v_cndmask_b32_e64 v21, 0, v206, s[8:9]
	v_sub_f32_e32 v18, v18, v21
	v_sub_f32_e32 v18, v20, v18
	v_fmamk_f32 v78, v18, 0x3d800000, v77
	v_mul_f32_e32 v18, 0x4b800000, v19
	v_cndmask_b32_e64 v18, v19, v18, s[6:7]
	v_rsq_f32_e32 v18, v18
	s_nop 0
	v_mul_f32_e32 v19, 0x45800000, v18
	v_cndmask_b32_e64 v28, v18, v19, s[6:7]
	s_or_b32 s4, s12, 4
	s_ashr_i32 s5, s4, 31
	s_lshl_b64 s[4:5], s[4:5], 6
	s_add_u32 s4, s68, s4
	s_addc_u32 s5, s69, s5
	s_waitcnt vmcnt(3)
	v_mul_f32_e32 v19, v74, v135
	s_waitcnt vmcnt(2)
	v_mul_f32_e32 v25, v70, v131
	v_fmac_f32_e32 v25, v65, v130
	s_waitcnt vmcnt(0)
; __device__ __forceinline__ void gla_b(const Args& a, int l, int row0, int h, LAS unsigned char* L, int tid) {
;     ...
;     for (int i = 0; i < 8; ++i) {
;         const int row = row0 + 8 * tg + i;
;         const float sc = rsqrtf(ssq[row] * (1.0f / D) + EPS);
;         const f32x4 a0 = *(const f32x4*)(ALRP + (size_t)row * 16), a1 = *(const f32x4*)(ALRP + (size_t)row * 16 + 4), a2 = *(const f32x4*)(ALRP + (size_t)row * 16 + 8), a3 = *(const f32x4*)(ALRP + (size_t)row * 16 + 12);
;         float x = (a0[0] * wa[0] + a0[1] * wa[1]) + (a0[2] * wa[2] + a0[3] * wa[3]);
;         x += (a1[0] * wa[4] + a1[1] * wa[5]) + (a1[2] * wa[6] + a1[3] * wa[7]);
;         x += (a2[0] * wa[8] + a2[1] * wa[9]) + (a2[2] * wa[10] + a2[3] * wa[11]);
;         x += (a3[0] * wa[12] + a3[1] * wa[13]) + (a3[2] * wa[14] + a3[3] * wa[15]);
;         x = x * sc + ba;
;         const float ls = fminf(x, 0.f) - __logf(1.0f + __expf(-fabsf(x)));
;         run += ls * (1.0f / 16.0f); bl[i] = run;
;     }
	v_mul_f32_e32 v29, v62, v123
	v_mul_f32_e32 v79, v61, v125
	v_fmac_f32_e32 v29, v37, v122
	v_fmac_f32_e32 v79, v31, v124
	v_add_f32_e32 v29, v29, v79
	v_mul_f32_e32 v79, v66, v127
	v_fmac_f32_e32 v79, v63, v126
	v_mul_f32_e32 v80, v68, v129
	v_fmac_f32_e32 v80, v64, v128
	v_mul_f32_e32 v24, v73, v133
	v_add_f32_e32 v79, v79, v80
	v_fmac_f32_e32 v24, v67, v132
	v_fmac_f32_e32 v19, v71, v134
	v_mul_f32_e32 v18, v72, v137
	v_add_f32_e32 v29, v29, v79
	v_add_f32_e32 v24, v25, v24
	v_fmac_f32_e32 v18, v69, v136
	v_add_f32_e32 v24, v29, v24
	v_add_f32_e32 v18, v19, v18
	v_add_f32_e32 v18, v24, v18
	v_fma_f32 v18, v28, v18, v75
	v_min_f32_e32 v19, 0, v18
	v_mul_f32_e64 v18, |v18|, s13
	v_exp_f32_e32 v18, v18
	s_nop 0
	v_add_f32_e32 v18, 1.0, v18
	v_cmp_gt_f32_e64 s[6:7], s3, v18
	s_nop 1
	v_cndmask_b32_e64 v20, 0, 32, s[6:7]
	v_ldexp_f32 v18, v18, v20
	v_log_f32_e32 v18, v18
	s_nop 0
	v_mul_f32_e32 v20, 0x3f317217, v18
	v_fma_f32 v20, v18, s22, -v20
	v_fmac_f32_e32 v20, 0x3377d1cf, v18
	v_fmac_f32_e32 v20, 0x3f317217, v18
	v_cmp_lt_f32_e64 s[8:9], |v18|, s36
	s_nop 1
	v_cndmask_b32_e64 v18, v18, v20, s[8:9]
	v_cndmask_b32_e64 v20, 0, v206, s[6:7]
	v_sub_f32_e32 v18, v18, v20
	v_sub_f32_e32 v18, v19, v18
	v_fmamk_f32 v79, v18, 0x3d800000, v78
	v_cmp_gt_f32_e64 s[8:9], s3, v14
	s_or_b32 s4, s12, 5
	s_ashr_i32 s5, s4, 31
	s_lshl_b64 s[4:5], s[4:5], 6
	s_add_u32 s4, s68, s4
	s_addc_u32 s5, s69, s5
	v_cmp_gt_f32_e64 s[6:7], s3, v15
	s_waitcnt vmcnt(3)
	v_mul_f32_e32 v19, v74, v151
	v_fmac_f32_e32 v19, v71, v150
	v_mul_f32_e32 v18, v72, v153
	s_waitcnt vmcnt(0)
	v_mul_f32_e32 v28, v62, v139
	v_mul_f32_e32 v29, v61, v141
	v_fmac_f32_e32 v18, v69, v152
	v_fmac_f32_e32 v28, v37, v138
	v_fmac_f32_e32 v29, v31, v140
	v_add_f32_e32 v18, v19, v18
	v_mul_f32_e32 v19, 0x4b800000, v14
	v_add_f32_e32 v28, v28, v29
	v_mul_f32_e32 v29, v66, v143
	v_cndmask_b32_e64 v14, v14, v19, s[8:9]
	v_fmac_f32_e32 v29, v63, v142
	v_mul_f32_e32 v80, v68, v145
	v_mul_f32_e32 v25, v70, v147
	v_rsq_f32_e32 v14, v14
	v_fmac_f32_e32 v80, v64, v144
	v_fmac_f32_e32 v25, v65, v146
	v_mul_f32_e32 v24, v73, v149
	v_add_f32_e32 v29, v29, v80
	v_fmac_f32_e32 v24, v67, v148
	v_add_f32_e32 v28, v28, v29
	v_add_f32_e32 v24, v25, v24
	v_add_f32_e32 v24, v28, v24
	v_mul_f32_e32 v19, 0x45800000, v14
	v_add_f32_e32 v18, v24, v18
	v_cndmask_b32_e64 v14, v14, v19, s[8:9]
	v_fma_f32 v14, v14, v18, v75
	v_min_f32_e32 v18, 0, v14
	v_mul_f32_e64 v14, |v14|, s13
	v_exp_f32_e32 v14, v14
	s_nop 0
	v_add_f32_e32 v14, 1.0, v14
	v_cmp_gt_f32_e64 s[8:9], s3, v14
	s_nop 1
	v_cndmask_b32_e64 v19, 0, 32, s[8:9]
	v_ldexp_f32 v14, v14, v19
	v_log_f32_e32 v14, v14
	s_nop 0
	v_mul_f32_e32 v19, 0x3f317217, v14
	v_fma_f32 v19, v14, s22, -v19
	v_fmac_f32_e32 v19, 0x3377d1cf, v14
	v_fmac_f32_e32 v19, 0x3f317217, v14
	v_cmp_lt_f32_e64 s[10:11], |v14|, s36
	s_nop 1
	v_cndmask_b32_e64 v14, v14, v19, s[10:11]
	v_cndmask_b32_e64 v19, 0, v206, s[8:9]
	v_sub_f32_e32 v14, v14, v19
	v_sub_f32_e32 v14, v18, v14
	v_fmamk_f32 v80, v14, 0x3d800000, v79
	v_mul_f32_e32 v14, 0x4b800000, v15
	v_cndmask_b32_e64 v14, v15, v14, s[6:7]
	v_rsq_f32_e32 v14, v14
	s_or_b32 s4, s12, 6
	s_ashr_i32 s5, s4, 31
	s_lshl_b64 s[4:5], s[4:5], 6
	v_mul_f32_e32 v15, 0x45800000, v14
	v_cndmask_b32_e64 v14, v14, v15, s[6:7]
	s_add_u32 s4, s68, s4
	s_addc_u32 s5, s69, s5
	s_waitcnt vmcnt(3)
	v_mul_f32_e32 v19, v74, v179
	s_waitcnt vmcnt(2)
	v_mul_f32_e32 v25, v70, v175
	s_waitcnt vmcnt(1)
	v_mul_f32_e32 v29, v68, v161
	s_waitcnt vmcnt(0)
	v_mul_f32_e32 v15, v62, v155
	v_mul_f32_e32 v28, v61, v157
	v_fmac_f32_e32 v15, v37, v154
	v_fmac_f32_e32 v28, v31, v156
	v_add_f32_e32 v15, v15, v28
	v_mul_f32_e32 v28, v66, v159
	v_fmac_f32_e32 v28, v63, v158
	v_fmac_f32_e32 v29, v64, v160
	v_fmac_f32_e32 v25, v65, v174
	v_mul_f32_e32 v24, v73, v177
	v_add_f32_e32 v28, v28, v29
	v_fmac_f32_e32 v24, v67, v176
	v_fmac_f32_e32 v19, v71, v178
	v_mul_f32_e32 v18, v72, v181
	v_add_f32_e32 v15, v15, v28
	v_add_f32_e32 v24, v25, v24
	v_fmac_f32_e32 v18, v69, v180
	v_add_f32_e32 v15, v15, v24
	v_add_f32_e32 v18, v19, v18
	v_add_f32_e32 v15, v15, v18
	v_fma_f32 v14, v14, v15, v75
	v_min_f32_e32 v15, 0, v14
	v_mul_f32_e64 v14, |v14|, s13
	v_exp_f32_e32 v14, v14
	s_nop 0
	v_add_f32_e32 v14, 1.0, v14
	v_cmp_gt_f32_e64 s[6:7], s3, v14
	s_nop 1
	v_cndmask_b32_e64 v18, 0, 32, s[6:7]
	v_ldexp_f32 v14, v14, v18
	v_log_f32_e32 v14, v14
	s_nop 0
	v_mul_f32_e32 v18, 0x3f317217, v14
	v_fma_f32 v18, v14, s22, -v18
	v_fmac_f32_e32 v18, 0x3377d1cf, v14
	v_fmac_f32_e32 v18, 0x3f317217, v14
	v_cmp_lt_f32_e64 s[8:9], |v14|, s36
	s_nop 1
	v_cndmask_b32_e64 v14, v14, v18, s[8:9]
	v_cndmask_b32_e64 v18, 0, v206, s[6:7]
	v_sub_f32_e32 v14, v14, v18
	v_sub_f32_e32 v14, v15, v14
	v_fmamk_f32 v81, v14, 0x3d800000, v80
	s_or_b32 s4, s12, 7
	s_ashr_i32 s5, s4, 31
	s_lshl_b64 s[4:5], s[4:5], 6
	s_add_u32 s4, s68, s4
	s_addc_u32 s5, s69, s5
	s_waitcnt vmcnt(1)
; __device__ __forceinline__ void lds_barrier() { asm volatile("s_waitcnt lgkmcnt(0)\n\ts_barrier" ::: "memory"); }
; __device__ __forceinline__ void gla_b(const Args& a, int l, int row0, int h, LAS unsigned char* L, int tid) {
;     ...
;     for (int i = 0; i < 8; ++i) {
;         const int row = row0 + 8 * tg + i;
;         const float sc = rsqrtf(ssq[row] * (1.0f / D) + EPS);
;         const f32x4 a0 = *(const f32x4*)(ALRP + (size_t)row * 16), a1 = *(const f32x4*)(ALRP + (size_t)row * 16 + 4), a2 = *(const f32x4*)(ALRP + (size_t)row * 16 + 8), a3 = *(const f32x4*)(ALRP + (size_t)row * 16 + 12);
;         float x = (a0[0] * wa[0] + a0[1] * wa[1]) + (a0[2] * wa[2] + a0[3] * wa[3]);
;         x += (a1[0] * wa[4] + a1[1] * wa[5]) + (a1[2] * wa[6] + a1[3] * wa[7]);
;         x += (a2[0] * wa[8] + a2[1] * wa[9]) + (a2[2] * wa[10] + a2[3] * wa[11]);
;         x += (a3[0] * wa[12] + a3[1] * wa[13]) + (a3[2] * wa[14] + a3[3] * wa[15]);
;         x = x * sc + ba;
;         const float ls = fminf(x, 0.f) - __logf(1.0f + __expf(-fabsf(x)));
;         run += ls * (1.0f / 16.0f); bl[i] = run;
;     }
;     SEG[tg * 64 + d] = run;
;     lds_barrier();
;     float off = 0.f;
; #pragma unroll
;     for (int g = 0; g < 7; ++g) if (g < tg) off += SEG[g * 64 + d];
; #pragma unroll
;     for (int i = 0; i < 8; ++i) Bm[(8 * tg + i) * 64 + d] = bl[i] + off;
;     lds_barrier();
	v_mul_f32_e32 v28, v68, v189
	s_waitcnt vmcnt(0)
	v_mul_f32_e32 v14, v62, v183
	v_mul_f32_e32 v15, v61, v185
	v_fmac_f32_e32 v14, v37, v182
	v_fmac_f32_e32 v15, v31, v184
	v_add_f32_e32 v14, v14, v15
	v_mul_f32_e32 v15, v66, v187
	v_fmac_f32_e32 v15, v63, v186
	v_fmac_f32_e32 v28, v64, v188
	v_add_f32_e32 v15, v15, v28
	v_add_f32_e32 v14, v14, v15
	v_mul_f32_e32 v15, v70, v191
	v_fmac_f32_e32 v15, v65, v190
	v_mul_f32_e32 v24, v73, v193
	v_fmac_f32_e32 v24, v67, v192
	v_add_f32_e32 v15, v15, v24
	v_add_f32_e32 v14, v14, v15
	v_mul_f32_e32 v15, v74, v195
	v_fmac_f32_e32 v15, v71, v194
	v_mul_f32_e32 v18, v72, v197
	v_fmac_f32_e32 v18, v69, v196
	v_add_f32_e32 v15, v15, v18
	v_add_f32_e32 v18, v14, v15
	v_pk_fma_f32 v[14:15], v[16:17], s[40:41], v[22:23] op_sel_hi:[1,0,0]
	s_nop 0
	v_mul_f32_e32 v16, 0x4b800000, v14
	v_cmp_gt_f32_e64 s[8:9], s3, v14
	v_cmp_gt_f32_e64 s[6:7], s3, v15
	s_nop 0
	v_cndmask_b32_e64 v14, v14, v16, s[8:9]
	v_rsq_f32_e32 v14, v14
	s_nop 0
	v_mul_f32_e32 v16, 0x45800000, v14
	v_cndmask_b32_e64 v14, v14, v16, s[8:9]
	v_fma_f32 v14, v14, v18, v75
	v_min_f32_e32 v16, 0, v14
	v_mul_f32_e64 v14, |v14|, s13
	v_exp_f32_e32 v14, v14
	s_nop 0
	v_add_f32_e32 v14, 1.0, v14
	v_cmp_gt_f32_e64 s[8:9], s3, v14
	s_nop 1
	v_cndmask_b32_e64 v17, 0, 32, s[8:9]
	v_ldexp_f32 v14, v14, v17
	v_log_f32_e32 v14, v14
	s_nop 0
	v_mul_f32_e32 v17, 0x3f317217, v14
	v_fma_f32 v17, v14, s22, -v17
	v_fmac_f32_e32 v17, 0x3377d1cf, v14
	v_fmac_f32_e32 v17, 0x3f317217, v14
	v_cmp_lt_f32_e64 s[10:11], |v14|, s36
	s_nop 1
	v_cndmask_b32_e64 v14, v14, v17, s[10:11]
	v_cndmask_b32_e64 v17, 0, v206, s[8:9]
	v_sub_f32_e32 v14, v14, v17
	v_sub_f32_e32 v14, v16, v14
	v_fmamk_f32 v82, v14, 0x3d800000, v81
	v_mul_f32_e32 v14, 0x4b800000, v15
	v_cndmask_b32_e64 v14, v15, v14, s[6:7]
	v_rsq_f32_e32 v14, v14
	s_nop 0
	v_mul_f32_e32 v15, 0x45800000, v14
	v_cndmask_b32_e64 v83, v14, v15, s[6:7]
	global_load_dwordx4 v[14:17], v1, s[4:5] offset:48
	global_load_dwordx4 v[18:21], v1, s[4:5] offset:32
	global_load_dwordx4 v[22:25], v1, s[4:5] offset:16
	global_load_dwordx4 v[26:29], v1, s[4:5]
	s_and_b32 s4, s16, 0x3fffffc0
	s_cmp_lt_i32 s17, 1
	s_waitcnt vmcnt(3)
	v_mul_f32_e32 v15, v74, v15
	s_waitcnt vmcnt(2)
	v_mul_f32_e32 v19, v70, v19
	s_waitcnt vmcnt(1)
	v_mul_f32_e32 v23, v66, v23
	s_waitcnt vmcnt(0)
	v_mul_f32_e32 v27, v62, v27
	v_fmac_f32_e32 v27, v37, v26
	v_mul_f32_e32 v26, v61, v29
	v_fmac_f32_e32 v23, v63, v22
	v_mul_f32_e32 v22, v68, v25
	v_fmac_f32_e32 v26, v31, v28
	v_fmac_f32_e32 v22, v64, v24
	v_fmac_f32_e32 v19, v65, v18
	v_mul_f32_e32 v18, v73, v21
	v_add_f32_e32 v26, v27, v26
	v_add_f32_e32 v22, v23, v22
	v_fmac_f32_e32 v18, v67, v20
	v_fmac_f32_e32 v15, v71, v14
	v_mul_f32_e32 v14, v72, v17
	v_add_f32_e32 v22, v26, v22
	v_add_f32_e32 v18, v19, v18
	v_fmac_f32_e32 v14, v69, v16
	v_add_f32_e32 v18, v22, v18
	v_add_f32_e32 v14, v15, v14
	v_add_f32_e32 v14, v18, v14
	v_fmac_f32_e32 v75, v83, v14
	v_mul_f32_e64 v15, |v75|, s13
	v_exp_f32_e32 v15, v15
	v_min_f32_e32 v14, 0, v75
	v_add_f32_e32 v15, 1.0, v15
	v_cmp_gt_f32_e64 s[6:7], s3, v15
	s_nop 1
	v_cndmask_b32_e64 v16, 0, 32, s[6:7]
	v_ldexp_f32 v15, v15, v16
	v_log_f32_e32 v15, v15
	s_nop 0
	v_mul_f32_e32 v16, 0x3f317217, v15
	v_fma_f32 v16, v15, s22, -v16
	v_fmac_f32_e32 v16, 0x3377d1cf, v15
	v_fmac_f32_e32 v16, 0x3f317217, v15
	v_cmp_lt_f32_e64 s[8:9], |v15|, s36
	s_nop 1
	v_cndmask_b32_e64 v15, v15, v16, s[8:9]
	v_cndmask_b32_e64 v16, 0, v206, s[6:7]
	v_sub_f32_e32 v15, v15, v16
	v_sub_f32_e32 v14, v14, v15
	v_fmamk_f32 v14, v14, 0x3d800000, v82
	v_lshl_add_u32 v15, s4, 2, v39
	ds_write_b32 v15, v14 offset:24832
	s_waitcnt lgkmcnt(0)
	s_barrier
	s_cbranch_scc1 .LBB0_918
	ds_read_b32 v15, v39 offset:24832
	s_waitcnt lgkmcnt(0)
	v_add_f32_e32 v15, 0, v15
	s_cmp_lt_i32 s17, 2
	s_cbranch_scc1 .LBB0_906
